# compressed-kv output normalisation rows: both loads issued before a single wait
# baseline (speedup 1.0000x reference)
.LBB0_128:
	v_ashrrev_i32_e32 v5, 31, v4
	v_lshl_add_u64 v[10:11], v[4:5], 4, s[12:13]
	flat_load_dwordx4 v[18:21], v[10:11]
	v_ashrrev_i32_e32 v5, 7, v4
	v_and_b32_e32 v5, -2, v5
	v_add_u32_e32 v10, s39, v5
	v_ashrrev_i32_e32 v11, 31, v10
	v_and_b32_e32 v5, 0xff00, v8
	v_lshlrev_b64 v[10:11], 18, v[10:11]
	v_lshl_add_u64 v[10:11], s[40:41], 0, v[10:11]
	v_lshlrev_b32_e32 v152, 2, v5
	v_lshl_add_u64 v[10:11], v[10:11], 0, v[152:153]
	v_mov_b32_e32 v7, v153
	v_lshl_add_u64 v[16:17], v[10:11], 0, v[6:7]
	flat_load_dwordx4 v[10:13], v[16:17]
	s_waitcnt vmcnt(0) lgkmcnt(0)
	v_mov_b32_e32 v14, v19
	v_mov_b32_e32 v15, v20
	v_mov_b32_e32 v19, v21
	v_pk_add_f32 v[18:19], v[14:15], v[18:19]
	s_nop 0
	v_add_f32_e32 v5, v18, v19
	v_fmamk_f32 v5, v5, 0x3b800000, v207
	v_cmp_gt_f32_e32 vcc, s68, v5
	v_mul_f32_e32 v7, 0x4b800000, v5
	s_nop 0
	v_cndmask_b32_e32 v5, v5, v7, vcc
	v_rsq_f32_e32 v5, v5
	s_nop 0
	v_mul_f32_e32 v7, 0x45800000, v5
	v_cndmask_b32_e32 v14, v5, v7, vcc
	v_add_u32_e32 v4, s38, v4
	v_cmp_lt_i32_e32 vcc, s33, v4
	v_add_u32_e32 v8, s2, v8
	s_or_b64 s[10:11], vcc, s[10:11]
	v_pk_mul_f32 v[10:11], v[10:11], v[14:15] op_sel_hi:[1,0]
	v_pk_mul_f32 v[12:13], v[12:13], v[14:15] op_sel_hi:[1,0]
	v_pk_mul_f32 v[10:11], v[0:1], v[10:11]
	v_pk_mul_f32 v[12:13], v[2:3], v[12:13]
	flat_store_dwordx4 v[16:17], v[10:13]
	s_andn2_b64 exec, exec, s[10:11]
	s_cbranch_execnz .LBB0_128
